# P1 rmsnorm rows: norm weights loaded once per phase (were re-loaded per row behind vmcnt(0) waits), the row's four float4 loads issued together
# speedup vs baseline: 1.0246x; 1.0033x over previous
; __device__ __forceinline__ unsigned pack2(float a, float b) { return (unsigned)f2bf(a) | ((unsigned)f2bf(b) << 16); }
; __device__ __forceinline__ int otid() { int t = threadIdx.x; asm volatile("" : "+v"(t)); return t; }
; __device__ __forceinline__ void phase_norm_convert(const Params& p, int l, char* smem) {
;   const int tid = otid(), lane = tid & 63, wave = tid >> 6;
;   float* X = (float*)(p.ws + OFF_X);
;   bf16_t* H = (bf16_t*)(p.ws + OFF_H);
;   const int n_row_items = NT / 4;
;   const int n_in = (NPAD / 64) * 16, n_br = 3 * 16 * 8, n_out = 16 * 16;
;   const int n_lora = 16;
;   const int total = n_row_items + n_in + n_br + n_out + n_lora;
;   for (int it = blockIdx.x; it < total; it += gridDim.x) {
;     if (it < n_row_items) {
;       const int row = it * 4 + wave;
;       const float* src;
;       if (l == 0) {
;         if (row < NTP) {
;           const int b = row / LP, t = row - b * LP;
;           src = (t < 16) ? (p.in[8] + (size_t)t * 1024) : (p.in[0] + ((size_t)b * 2048 + (t - 16)) * 1024);
;         } else {
;           src = p.in[1] + (size_t)(row - NTP) * 1024;
;         }
;       } else {
;         src = X + (size_t)row * 1024;
;       }
;       float4 v[4];
;       float ss = 0.f;
; #pragma unroll
;       for (int i = 0; i < 4; ++i) {
;         v[i] = ((const float4*)src)[lane + 64 * i];
;         ss += v[i].x * v[i].x + v[i].y * v[i].y + v[i].z * v[i].z + v[i].w * v[i].w;
;       }
;       ss = wave_sum(ss);
;       const float rs = rsqrtf(ss * (1.f / 1024.f) + 1e-6f);
;       const float4* nw = (const float4*)(p.in[9] + (size_t)l * 1024);
; #pragma unroll
;       for (int i = 0; i < 4; ++i) {
;         if (l == 0) ((float4*)(X + (size_t)row * 1024))[lane + 64 * i] = v[i];
;         const float4 w = nw[lane + 64 * i];
;         uint2 o;
;         o.x = pack2(v[i].x * rs * w.x, v[i].y * rs * w.y);
;         o.y = pack2(v[i].z * rs * w.z, v[i].w * rs * w.w);
;         *(uint2*)(H + (size_t)row * 1024 + (lane + 64 * i) * 4) = o;
.LBB0_728:
	s_andn2_b64 vcc, exec, s[12:13]
	s_cbranch_vccnz .LBB0_831
	v_readlane_b32 s0, v243, 46
	v_readlane_b32 s1, v243, 47
	v_mov_b32_e32 v0, v178
	s_andn2_b64 vcc, exec, s[0:1]
	s_cbranch_vccnz .LBB0_831
	v_readlane_b32 s0, v241, 22
	s_mov_b32 s26, s0
	s_ashr_i32 s27, s0, 31
	v_readlane_b32 s0, v241, 21
	s_lshl_b64 s[12:13], s[26:27], 17
	s_lshl_b64 s[24:25], s[26:27], 22
	s_lshl_b64 s[14:15], s[26:27], 21
	s_add_i32 s18, s0, 6
	s_cmp_lt_u32 s18, 13
	s_cselect_b64 s[16:17], -1, 0
	s_cmp_gt_u32 s18, 12
	s_cselect_b64 s[22:23], -1, 0
	s_lshl_b64 s[26:27], s[26:27], 12
	s_add_u32 s24, s4, s24
	v_readlane_b32 s40, v244, 34
	v_ashrrev_i32_e32 v1, 6, v0
	v_and_b32_e32 v0, 63, v0
	s_addc_u32 s25, s5, s25
	v_readlane_b32 s42, v244, 36
	v_lshlrev_b32_e32 v4, 2, v0
	v_readlane_b32 s43, v244, 37
	s_add_u32 s26, s42, s26
	v_or_b32_e32 v6, 0x100, v4
	v_or_b32_e32 v8, 0x200, v4
	v_or_b32_e32 v10, 0x300, v4
	s_addc_u32 s27, s43, s27
	v_lshlrev_b32_e32 v2, 4, v0
	v_lshl_add_u64 v[20:21], s[26:27], 0, v[2:3]
	s_waitcnt vmcnt(6)
	v_lshlrev_b32_e32 v22, 1, v4
	v_lshlrev_b32_e32 v24, 1, v6
	v_lshlrev_b32_e32 v26, 1, v8
	s_waitcnt vmcnt(4)
	v_lshlrev_b32_e32 v28, 1, v10
	v_readlane_b32 s30, v244, 0
	v_readlane_b32 s1, v241, 23
	v_readlane_b32 s41, v244, 35
	v_readlane_b32 s44, v244, 38
	v_readlane_b32 s45, v244, 39
	v_readlane_b32 s46, v244, 40
	v_readlane_b32 s47, v244, 41
	global_load_dwordx4 v[188:191], v[20:21], off
	global_load_dwordx4 v[192:195], v[20:21], off offset:1024
	global_load_dwordx4 v[196:199], v[20:21], off offset:2048
	global_load_dwordx4 v[200:203], v[20:21], off offset:3072
	s_waitcnt vmcnt(0)
	s_branch .LBB0_733
.LBB0_731:
	v_mov_b32_e32 v9, v6
	v_mov_b32_e32 v6, v5
	v_mov_b32_e32 v8, v4
	v_pk_mul_f32 v[10:11], v[6:7], v[30:31]
	v_mov_b32_e32 v4, v200
	v_mov_b32_e32 v5, v201
	v_mov_b32_e32 v6, v202
	v_mov_b32_e32 v7, v203
	v_pk_mul_f32 v[8:9], v[8:9], v[30:31]
	v_mov_b32_e32 v29, v3
	v_lshl_add_u64 v[12:13], v[16:17], 0, v[28:29]
	v_mov_b32_e32 v14, v4
	v_mov_b32_e32 v15, v6
	v_pk_mul_f32 v[8:9], v[8:9], v[14:15]
	v_mov_b32_e32 v6, v5
	v_pk_mul_f32 v[4:5], v[10:11], v[6:7]
	v_and_b32_sdwa v6, v8, v183 dst_sel:DWORD dst_unused:UNUSED_PAD src0_sel:WORD_1 src1_sel:DWORD
	v_add3_u32 v6, v8, v6, s37
	v_and_b32_sdwa v7, v5, v183 dst_sel:DWORD dst_unused:UNUSED_PAD src0_sel:WORD_1 src1_sel:DWORD
	v_and_b32_sdwa v8, v4, v183 dst_sel:DWORD dst_unused:UNUSED_PAD src0_sel:WORD_1 src1_sel:DWORD
	v_and_b32_sdwa v2, v9, v183 dst_sel:DWORD dst_unused:UNUSED_PAD src0_sel:WORD_1 src1_sel:DWORD
	v_add3_u32 v5, v5, v7, s37
	v_add3_u32 v4, v4, v8, s37
	v_add3_u32 v2, v9, v2, s37
	v_and_b32_e32 v5, 0xffff0000, v5
	v_and_b32_e32 v4, 0xffff0000, v4
	v_or_b32_sdwa v5, v5, v2 dst_sel:DWORD dst_unused:UNUSED_PAD src0_sel:DWORD src1_sel:WORD_1
	v_or_b32_sdwa v4, v4, v6 dst_sel:DWORD dst_unused:UNUSED_PAD src0_sel:DWORD src1_sel:WORD_1
	global_store_dwordx2 v[12:13], v[4:5], off

; __device__ __forceinline__ unsigned pack2(float a, float b) { return (unsigned)f2bf(a) | ((unsigned)f2bf(b) << 16); }
; __device__ __forceinline__ void phase_norm_convert(const Params& p, int l, char* smem) {
;     ...
;       float4 v[4];
;       float ss = 0.f;
; #pragma unroll
;       for (int i = 0; i < 4; ++i) {
;         v[i] = ((const float4*)src)[lane + 64 * i];
;         ss += v[i].x * v[i].x + v[i].y * v[i].y + v[i].z * v[i].z + v[i].w * v[i].w;
;       }
;       ss = wave_sum(ss);
;       const float rs = rsqrtf(ss * (1.f / 1024.f) + 1e-6f);
;       const float4* nw = (const float4*)(p.in[9] + (size_t)l * 1024);
; #pragma unroll
;       for (int i = 0; i < 4; ++i) {
;         if (l == 0) ((float4*)(X + (size_t)row * 1024))[lane + 64 * i] = v[i];
;         const float4 w = nw[lane + 64 * i];
;         uint2 o;
;         o.x = pack2(v[i].x * rs * w.x, v[i].y * rs * w.y);
;         o.y = pack2(v[i].z * rs * w.z, v[i].w * rs * w.w);
;         *(uint2*)(H + (size_t)row * 1024 + (lane + 64 * i) * 4) = o;
.LBB0_823:
	v_lshlrev_b64 v[4:5], 12, v[4:5]
	v_lshl_add_u64 v[4:5], v[6:7], 0, v[4:5]
	v_lshlrev_b32_e32 v2, 4, v0
	v_lshl_add_u64 v[4:5], v[4:5], 0, v[2:3]
	global_load_dwordx4 v[16:19], v[4:5], off
	global_load_dwordx4 v[12:15], v[4:5], off offset:1024
	global_load_dwordx4 v[204:207], v[4:5], off offset:2048
	global_load_dwordx4 v[208:211], v[4:5], off offset:3072
	s_andn2_b64 vcc, exec, s[16:17]
	s_waitcnt vmcnt(3)
	v_mov_b32_e32 v8, v17
	s_waitcnt vmcnt(2)
	v_mov_b32_e32 v9, v13
	v_mov_b32_e32 v6, v16
	v_mov_b32_e32 v7, v12
	v_pk_mul_f32 v[8:9], v[8:9], v[8:9]
	s_nop 0
	v_pk_fma_f32 v[6:7], v[6:7], v[6:7], v[8:9]
	v_mov_b32_e32 v8, v18
	v_mov_b32_e32 v9, v14
	v_pk_fma_f32 v[6:7], v[8:9], v[8:9], v[6:7]
	v_mov_b32_e32 v8, v19
	v_mov_b32_e32 v9, v15
	v_pk_fma_f32 v[32:33], v[8:9], v[8:9], v[6:7]
	s_nop 0
	v_add_f32_e32 v23, v32, v33
	v_lshlrev_b64 v[32:33], 12, v[30:31]
	v_lshl_add_u64 v[32:33], s[10:11], 0, v[32:33]
	s_waitcnt vmcnt(1)
	v_mov_b32_e32 v8, v204
	v_mov_b32_e32 v9, v205
	v_mov_b32_e32 v10, v206
	v_mov_b32_e32 v11, v207
	v_mov_b32_e32 v36, v9
	s_waitcnt vmcnt(0)
	v_mov_b32_e32 v4, v208
	v_mov_b32_e32 v5, v209
	v_mov_b32_e32 v6, v210
	v_mov_b32_e32 v7, v211
	v_mov_b32_e32 v37, v5
	v_mov_b32_e32 v34, v8
	v_mov_b32_e32 v35, v4
	v_pk_mul_f32 v[36:37], v[36:37], v[36:37]
	s_nop 0
	v_pk_fma_f32 v[34:35], v[34:35], v[34:35], v[36:37]
	v_mov_b32_e32 v36, v10
	v_mov_b32_e32 v37, v6
	v_pk_fma_f32 v[34:35], v[36:37], v[36:37], v[34:35]
	v_mov_b32_e32 v36, v11
	v_mov_b32_e32 v37, v7
	v_pk_fma_f32 v[34:35], v[36:37], v[36:37], v[34:35]
	s_nop 0
	v_add_f32_e32 v23, v23, v34
	v_add_f32_e32 v23, v23, v35
	s_nop 1
	v_add_f32_dpp v23, v23, v23 quad_perm:[1,0,3,2] row_mask:0xf bank_mask:0xf bound_ctrl:1
	s_nop 1
	v_add_f32_dpp v23, v23, v23 quad_perm:[2,3,0,1] row_mask:0xf bank_mask:0xf bound_ctrl:1
	s_nop 1
	v_add_f32_dpp v23, v23, v23 row_half_mirror row_mask:0xf bank_mask:0xf bound_ctrl:1
	s_nop 1
	v_add_f32_dpp v23, v23, v23 row_mirror row_mask:0xf bank_mask:0xf bound_ctrl:1
	s_nop 0
	v_readlane_b32 s26, v23, 0
	v_readlane_b32 s18, v23, 16
	v_readlane_b32 s27, v23, 32
	v_readlane_b32 s28, v23, 48
	v_cndmask_b32_e64 v23, 0, 1, s[16:17]
	v_cmp_ne_u32_e64 s[40:41], 1, v23
	s_cbranch_vccnz .LBB0_825
	v_lshl_add_u64 v[34:35], v[32:33], 0, v[2:3]
	global_store_dwordx4 v[34:35], v[16:19], off
.LBB0_825:
	v_mov_b32_e32 v34, v188
	v_mov_b32_e32 v35, v189
	v_mov_b32_e32 v36, v190
	v_mov_b32_e32 v37, v191
	v_mov_b32_e32 v38, s18
	v_mov_b32_e32 v39, s28
	v_mov_b32_e32 v40, v16
	v_mov_b32_e32 v41, v18
	v_mov_b32_e32 v18, v17
	v_pk_add_f32 v[16:17], s[26:27], v[38:39]
	v_readlane_b32 s0, v241, 11
	v_add_f32_e32 v16, v16, v17
	v_fmamk_f32 v16, v16, 0x3a800000, v180
	v_mul_f32_e32 v17, 0x4b800000, v16
	v_cmp_gt_f32_e32 vcc, s72, v16
	v_lshlrev_b64 v[30:31], 11, v[30:31]
	v_readlane_b32 s1, v241, 12
	v_cndmask_b32_e32 v16, v16, v17, vcc
	v_rsq_f32_e32 v25, v16
	v_mov_b32_e32 v23, v3
	v_lshl_add_u64 v[16:17], s[0:1], 0, v[30:31]
	v_lshl_add_u64 v[38:39], v[16:17], 0, v[22:23]
	v_mul_f32_e32 v23, 0x45800000, v25
	v_cndmask_b32_e32 v30, v25, v23, vcc
	v_pk_mul_f32 v[18:19], v[18:19], v[30:31] op_sel_hi:[1,0]
	v_pk_mul_f32 v[40:41], v[40:41], v[30:31] op_sel_hi:[1,0]
	s_and_b64 vcc, exec, s[40:41]
	v_mov_b32_e32 v43, v36
	v_mov_b32_e32 v36, v35
	v_mov_b32_e32 v42, v34
	v_pk_mul_f32 v[18:19], v[18:19], v[36:37]
	v_pk_mul_f32 v[34:35], v[40:41], v[42:43]
	v_and_b32_sdwa v27, v19, v183 dst_sel:DWORD dst_unused:UNUSED_PAD src0_sel:WORD_1 src1_sel:DWORD
	v_and_b32_sdwa v29, v18, v183 dst_sel:DWORD dst_unused:UNUSED_PAD src0_sel:WORD_1 src1_sel:DWORD
	v_and_b32_sdwa v23, v35, v183 dst_sel:DWORD dst_unused:UNUSED_PAD src0_sel:WORD_1 src1_sel:DWORD
	v_and_b32_sdwa v25, v34, v183 dst_sel:DWORD dst_unused:UNUSED_PAD src0_sel:WORD_1 src1_sel:DWORD
	v_add3_u32 v19, v19, v27, s37
	v_add3_u32 v18, v18, v29, s37
	v_add3_u32 v25, v34, v25, s37
	v_add3_u32 v23, v35, v23, s37
	v_and_b32_e32 v19, 0xffff0000, v19
	v_and_b32_e32 v18, 0xffff0000, v18
	v_or_b32_sdwa v19, v19, v23 dst_sel:DWORD dst_unused:UNUSED_PAD src0_sel:DWORD src1_sel:WORD_1
	v_or_b32_sdwa v18, v18, v25 dst_sel:DWORD dst_unused:UNUSED_PAD src0_sel:DWORD src1_sel:WORD_1
	global_store_dwordx2 v[38:39], v[18:19], off
	s_cbranch_vccnz .LBB0_827
	v_lshl_add_u64 v[18:19], v[32:33], 0, v[2:3]
	global_store_dwordx4 v[18:19], v[12:15], off offset:1024
; __device__ __forceinline__ unsigned pack2(float a, float b) { return (unsigned)f2bf(a) | ((unsigned)f2bf(b) << 16); }
; __device__ __forceinline__ void phase_norm_convert(const Params& p, int l, char* smem) {
;     ...
; #pragma unroll
;       for (int i = 0; i < 4; ++i) {
;         if (l == 0) ((float4*)(X + (size_t)row * 1024))[lane + 64 * i] = v[i];
;         const float4 w = nw[lane + 64 * i];
;         uint2 o;
;         o.x = pack2(v[i].x * rs * w.x, v[i].y * rs * w.y);
;         o.y = pack2(v[i].z * rs * w.z, v[i].w * rs * w.w);
;         *(uint2*)(H + (size_t)row * 1024 + (lane + 64 * i) * 4) = o;
;       }
.LBB0_827:
	v_mov_b32_e32 v34, v192
	v_mov_b32_e32 v35, v193
	v_mov_b32_e32 v36, v194
	v_mov_b32_e32 v37, v195
	v_mov_b32_e32 v31, v30
	v_mov_b32_e32 v19, v14
	v_mov_b32_e32 v14, v13
	v_mov_b32_e32 v18, v12
	v_pk_mul_f32 v[14:15], v[14:15], v[30:31]
	v_pk_mul_f32 v[12:13], v[18:19], v[30:31]
	v_mov_b32_e32 v25, v3
	v_lshl_add_u64 v[18:19], v[16:17], 0, v[24:25]
	s_and_b64 vcc, exec, s[40:41]
	v_mov_b32_e32 v39, v36
	v_mov_b32_e32 v36, v35
	v_mov_b32_e32 v38, v34
	v_pk_mul_f32 v[14:15], v[14:15], v[36:37]
	v_pk_mul_f32 v[12:13], v[12:13], v[38:39]
	v_and_b32_sdwa v27, v15, v183 dst_sel:DWORD dst_unused:UNUSED_PAD src0_sel:WORD_1 src1_sel:DWORD
	v_and_b32_sdwa v29, v14, v183 dst_sel:DWORD dst_unused:UNUSED_PAD src0_sel:WORD_1 src1_sel:DWORD
	v_and_b32_sdwa v23, v13, v183 dst_sel:DWORD dst_unused:UNUSED_PAD src0_sel:WORD_1 src1_sel:DWORD
	v_and_b32_sdwa v25, v12, v183 dst_sel:DWORD dst_unused:UNUSED_PAD src0_sel:WORD_1 src1_sel:DWORD
	v_add3_u32 v15, v15, v27, s37
	v_add3_u32 v14, v14, v29, s37
	v_add3_u32 v12, v12, v25, s37
	v_add3_u32 v13, v13, v23, s37
	v_and_b32_e32 v15, 0xffff0000, v15
	v_and_b32_e32 v14, 0xffff0000, v14
	v_or_b32_sdwa v13, v15, v13 dst_sel:DWORD dst_unused:UNUSED_PAD src0_sel:DWORD src1_sel:WORD_1
	v_or_b32_sdwa v12, v14, v12 dst_sel:DWORD dst_unused:UNUSED_PAD src0_sel:DWORD src1_sel:WORD_1
	global_store_dwordx2 v[18:19], v[12:13], off
	s_cbranch_vccnz .LBB0_829
	v_lshl_add_u64 v[12:13], v[32:33], 0, v[2:3]
	global_store_dwordx4 v[12:13], v[8:11], off offset:2048
.LBB0_829:
	v_mov_b32_e32 v12, v196
	v_mov_b32_e32 v13, v197
	v_mov_b32_e32 v14, v198
	v_mov_b32_e32 v15, v199
	v_mov_b32_e32 v19, v10
	v_mov_b32_e32 v10, v9
	v_mov_b32_e32 v18, v8
	v_pk_mul_f32 v[10:11], v[10:11], v[30:31]
	v_pk_mul_f32 v[8:9], v[18:19], v[30:31]
	v_mov_b32_e32 v27, v3
	v_lshl_add_u64 v[18:19], v[16:17], 0, v[26:27]
	s_and_b64 vcc, exec, s[40:41]
	v_mov_b32_e32 v35, v14
	v_mov_b32_e32 v14, v13
	v_mov_b32_e32 v34, v12
	v_pk_mul_f32 v[10:11], v[10:11], v[14:15]
	v_pk_mul_f32 v[8:9], v[8:9], v[34:35]
	v_and_b32_sdwa v14, v11, v183 dst_sel:DWORD dst_unused:UNUSED_PAD src0_sel:WORD_1 src1_sel:DWORD
	v_and_b32_sdwa v15, v10, v183 dst_sel:DWORD dst_unused:UNUSED_PAD src0_sel:WORD_1 src1_sel:DWORD
	v_and_b32_sdwa v12, v9, v183 dst_sel:DWORD dst_unused:UNUSED_PAD src0_sel:WORD_1 src1_sel:DWORD
	v_and_b32_sdwa v13, v8, v183 dst_sel:DWORD dst_unused:UNUSED_PAD src0_sel:WORD_1 src1_sel:DWORD
	v_add3_u32 v11, v11, v14, s37
	v_add3_u32 v10, v10, v15, s37
	v_add3_u32 v8, v8, v13, s37
	v_add3_u32 v9, v9, v12, s37
	v_and_b32_e32 v11, 0xffff0000, v11
	v_and_b32_e32 v10, 0xffff0000, v10
	v_or_b32_sdwa v9, v11, v9 dst_sel:DWORD dst_unused:UNUSED_PAD src0_sel:DWORD src1_sel:WORD_1
	v_or_b32_sdwa v8, v10, v8 dst_sel:DWORD dst_unused:UNUSED_PAD src0_sel:DWORD src1_sel:WORD_1
	global_store_dwordx2 v[18:19], v[8:9], off
	s_cbranch_vccnz .LBB0_731
	v_lshl_add_u64 v[8:9], v[32:33], 0, v[2:3]
	global_store_dwordx4 v[8:9], v[4:7], off offset:3072
	s_branch .LBB0_731
